# attention O store through a per-wave LDS transpose (8 full-row dwordx4 stores per unit) + down-GEMM residual epilogue with DPP row exchange (full 128-B lines per load/store)
# speedup vs baseline: 1.0146x; 1.0023x over previous
; DI int tid_opq() { int t = threadIdx.x; asm volatile("" : "+v"(t)); return t; }
; DI unsigned pk2(float lo, float hi) { const f32x2_t v = {lo, hi}; return __builtin_bit_cast(unsigned, __builtin_convertvector(v, bf16x2_t)); }
; DI void attn_unit(LAS unsigned char* lds, const bf16_t* Q, const bf16_t* Kn, const bf16_t* Kpe, const bf16_t* Vt, bf16_t* O, int b, int h, int qb) {
;     ...
;     const int tid2 = tid_opq(), lane2 = tid2 & 63, hi2 = lane2 >> 5;
;     const int qrow2 = b * 4096 + qb * 512 + __builtin_amdgcn_readfirstlane(tid2 >> 6) * 64 + (lane2 & 31);
; #pragma unroll
;     for (int j = 0; j < 2; ++j) {
;         const float l = lsum[j] + __shfl_xor(lsum[j], 32), inv = 1.0f / l;
;         bf16_t* op = O + (size_t)(qrow2 + 32 * j) * 1024 + h * 64;
; #pragma unroll
;         for (int g4 = 0; g4 < 4; ++g4) {
;             u32x2 w0, w1;
;             w0.x = pk2(o[j][0][4 * g4] * inv, o[j][0][4 * g4 + 1] * inv); w0.y = pk2(o[j][0][4 * g4 + 2] * inv, o[j][0][4 * g4 + 3] * inv);
;             w1.x = pk2(o[j][1][4 * g4] * inv, o[j][1][4 * g4 + 1] * inv); w1.y = pk2(o[j][1][4 * g4 + 2] * inv, o[j][1][4 * g4 + 3] * inv);
;             *(u32x2*)(op + 8 * g4 + 4 * hi2) = w0; *(u32x2*)(op + 32 + 8 * g4 + 4 * hi2) = w1;
;         }
;     }
.LBB0_1104:
	ds_bpermute_b32 v65, v240, v213
	v_mov_b32_e32 v67, v232
	ds_bpermute_b32 v80, v240, v212
	s_waitcnt lgkmcnt(1)
	v_add_f32_e32 v65, v213, v65
	v_div_scale_f32 v66, s[6:7], v65, v65, 1.0
	v_rcp_f32_e32 v68, v66
	v_readfirstlane_b32 s2, v67
	s_andn2_b32 s2, s2, 63
	s_add_i32 s2, s2, s9
	v_fma_f32 v69, -v66, v68, 1.0
	v_fmac_f32_e32 v68, v69, v68
	v_div_scale_f32 v69, vcc, 1.0, v65, 1.0
	v_mul_f32_e32 v70, v69, v68
	v_fma_f32 v71, -v66, v70, v69
	v_fmac_f32_e32 v70, v71, v68
	v_fma_f32 v66, -v66, v70, v69
	v_lshrrev_b32_e32 v121, 6, v67
	v_mul_u32_u24_e32 v121, 0x2400, v121
	v_add_u32_e32 v121, 0xc000, v121
	v_div_fmas_f32 v66, v66, v68, v70
	v_and_b32_e32 v120, 31, v233
	v_div_fixup_f32 v66, v66, v65, 1.0
	v_mul_u32_u24_e32 v120, 0x90, v120
	v_add_u32_e32 v120, v120, v121
	v_lshrrev_b32_e32 v64, 5, v233
	v_lshl_add_u32 v120, v64, 4, v120
	s_waitcnt lgkmcnt(0)
	v_add_f32_e32 v80, v212, v80
	v_div_scale_f32 v81, s[6:7], v80, v80, 1.0
	v_rcp_f32_e32 v84, v81
	s_nop 0
	v_fma_f32 v82, -v81, v84, 1.0
	v_fmac_f32_e32 v84, v82, v84
	v_div_scale_f32 v82, vcc, 1.0, v80, 1.0
	v_mul_f32_e32 v83, v82, v84
	v_fma_f32 v85, -v81, v83, v82
	v_fmac_f32_e32 v83, v85, v84
	v_fma_f32 v82, -v81, v83, v82
	v_lshrrev_b32_e32 v64, 3, v233
	v_div_fmas_f32 v82, v82, v84, v83
	v_mul_u32_u24_e32 v122, 0x90, v64
	v_add_u32_e32 v121, v122, v121
	v_div_fixup_f32 v82, v82, v80, 1.0
	v_and_b32_e32 v65, 7, v233
	v_lshl_add_u32 v121, v65, 4, v121
	v_add_u32_e32 v64, s2, v64
	s_lshl_b32 s2, s8, 7
	s_add_u32 s6, s79, s2
	s_addc_u32 s7, s86, 0
	v_lshlrev_b32_e32 v188, 4, v65
	v_ashrrev_i32_e32 v65, 31, v64
	v_lshlrev_b64 v[68:69], 11, v[64:65]
	v_lshl_add_u64 v[68:69], s[6:7], 0, v[68:69]
	v_lshl_add_u64 v[68:69], v[68:69], 0, v[188:189]
	v_pk_mul_f32 v[48:49], v[48:49], v[66:67] op_sel_hi:[1,0]
	v_pk_mul_f32 v[50:51], v[50:51], v[66:67] op_sel_hi:[1,0]
	v_pk_mul_f32 v[52:53], v[52:53], v[66:67] op_sel_hi:[1,0]
	v_pk_mul_f32 v[54:55], v[54:55], v[66:67] op_sel_hi:[1,0]
	v_cvt_pk_bf16_f32 v72, v48, v49
	v_cvt_pk_bf16_f32 v73, v50, v51
	v_cvt_pk_bf16_f32 v74, v52, v53
	v_cvt_pk_bf16_f32 v75, v54, v55
	s_nop 1
	v_permlane32_swap_b32_e32 v72, v74
	v_permlane32_swap_b32_e32 v73, v75
	ds_write_b128 v120, v[72:75] offset:0
	v_pk_mul_f32 v[56:57], v[56:57], v[66:67] op_sel_hi:[1,0]
	v_pk_mul_f32 v[58:59], v[58:59], v[66:67] op_sel_hi:[1,0]
	v_pk_mul_f32 v[60:61], v[60:61], v[66:67] op_sel_hi:[1,0]
	v_pk_mul_f32 v[62:63], v[62:63], v[66:67] op_sel_hi:[1,0]
	v_cvt_pk_bf16_f32 v76, v56, v57
	v_cvt_pk_bf16_f32 v77, v58, v59
	v_cvt_pk_bf16_f32 v78, v60, v61
	v_cvt_pk_bf16_f32 v79, v62, v63
	s_nop 1
	v_permlane32_swap_b32_e32 v76, v78
	v_permlane32_swap_b32_e32 v77, v79
	ds_write_b128 v120, v[76:79] offset:32
	v_pk_mul_f32 v[16:17], v[16:17], v[66:67] op_sel_hi:[1,0]
	v_pk_mul_f32 v[18:19], v[18:19], v[66:67] op_sel_hi:[1,0]
	v_pk_mul_f32 v[20:21], v[20:21], v[66:67] op_sel_hi:[1,0]
	v_pk_mul_f32 v[22:23], v[22:23], v[66:67] op_sel_hi:[1,0]
	v_cvt_pk_bf16_f32 v72, v16, v17
	v_cvt_pk_bf16_f32 v73, v18, v19
	v_cvt_pk_bf16_f32 v74, v20, v21
	v_cvt_pk_bf16_f32 v75, v22, v23
	s_nop 1
	v_permlane32_swap_b32_e32 v72, v74
	v_permlane32_swap_b32_e32 v73, v75
	ds_write_b128 v120, v[72:75] offset:64
	v_pk_mul_f32 v[24:25], v[24:25], v[66:67] op_sel_hi:[1,0]
	v_pk_mul_f32 v[26:27], v[26:27], v[66:67] op_sel_hi:[1,0]
	v_pk_mul_f32 v[28:29], v[28:29], v[66:67] op_sel_hi:[1,0]
	v_pk_mul_f32 v[30:31], v[30:31], v[66:67] op_sel_hi:[1,0]
	v_cvt_pk_bf16_f32 v76, v24, v25
	v_cvt_pk_bf16_f32 v77, v26, v27
	v_cvt_pk_bf16_f32 v78, v28, v29
	v_cvt_pk_bf16_f32 v79, v30, v31
	s_nop 1
	v_permlane32_swap_b32_e32 v76, v78
	v_permlane32_swap_b32_e32 v77, v79
	ds_write_b128 v120, v[76:79] offset:96
	v_pk_mul_f32 v[32:33], v[32:33], v[82:83] op_sel_hi:[1,0]
	v_pk_mul_f32 v[34:35], v[34:35], v[82:83] op_sel_hi:[1,0]
	v_pk_mul_f32 v[36:37], v[36:37], v[82:83] op_sel_hi:[1,0]
	v_pk_mul_f32 v[38:39], v[38:39], v[82:83] op_sel_hi:[1,0]
	v_cvt_pk_bf16_f32 v72, v32, v33
	v_cvt_pk_bf16_f32 v73, v34, v35
	v_cvt_pk_bf16_f32 v74, v36, v37
	v_cvt_pk_bf16_f32 v75, v38, v39
	s_nop 1
	v_permlane32_swap_b32_e32 v72, v74
	v_permlane32_swap_b32_e32 v73, v75
	ds_write_b128 v120, v[72:75] offset:4608
	v_pk_mul_f32 v[40:41], v[40:41], v[82:83] op_sel_hi:[1,0]
	v_pk_mul_f32 v[42:43], v[42:43], v[82:83] op_sel_hi:[1,0]
	v_pk_mul_f32 v[44:45], v[44:45], v[82:83] op_sel_hi:[1,0]
	v_pk_mul_f32 v[46:47], v[46:47], v[82:83] op_sel_hi:[1,0]
	v_cvt_pk_bf16_f32 v76, v40, v41
	v_cvt_pk_bf16_f32 v77, v42, v43
	v_cvt_pk_bf16_f32 v78, v44, v45
	v_cvt_pk_bf16_f32 v79, v46, v47
	s_nop 1
	v_permlane32_swap_b32_e32 v76, v78
	v_permlane32_swap_b32_e32 v77, v79
	ds_write_b128 v120, v[76:79] offset:4640
	v_pk_mul_f32 v[0:1], v[0:1], v[82:83] op_sel_hi:[1,0]
	v_pk_mul_f32 v[2:3], v[2:3], v[82:83] op_sel_hi:[1,0]
	v_pk_mul_f32 v[4:5], v[4:5], v[82:83] op_sel_hi:[1,0]
	v_pk_mul_f32 v[6:7], v[6:7], v[82:83] op_sel_hi:[1,0]
	v_cvt_pk_bf16_f32 v72, v0, v1
	v_cvt_pk_bf16_f32 v73, v2, v3
	v_cvt_pk_bf16_f32 v74, v4, v5
	v_cvt_pk_bf16_f32 v75, v6, v7
	s_nop 1
	v_permlane32_swap_b32_e32 v72, v74
	v_permlane32_swap_b32_e32 v73, v75
	ds_write_b128 v120, v[72:75] offset:4672
	v_pk_mul_f32 v[8:9], v[8:9], v[82:83] op_sel_hi:[1,0]
	v_pk_mul_f32 v[10:11], v[10:11], v[82:83] op_sel_hi:[1,0]
	v_pk_mul_f32 v[12:13], v[12:13], v[82:83] op_sel_hi:[1,0]
	v_pk_mul_f32 v[14:15], v[14:15], v[82:83] op_sel_hi:[1,0]
	v_cvt_pk_bf16_f32 v76, v8, v9
	v_cvt_pk_bf16_f32 v77, v10, v11
	v_cvt_pk_bf16_f32 v78, v12, v13
	v_cvt_pk_bf16_f32 v79, v14, v15
	s_nop 1
	v_permlane32_swap_b32_e32 v76, v78
	v_permlane32_swap_b32_e32 v77, v79
	ds_write_b128 v120, v[76:79] offset:4704
	ds_read_b128 v[88:91], v121
	ds_read_b128 v[92:95], v121 offset:1152
	ds_read_b128 v[96:99], v121 offset:2304
	ds_read_b128 v[100:103], v121 offset:3456
	ds_read_b128 v[104:107], v121 offset:4608
	ds_read_b128 v[108:111], v121 offset:5760
	ds_read_b128 v[112:115], v121 offset:6912
	ds_read_b128 v[116:119], v121 offset:8064
	s_mov_b64 vcc, 0x4000
	s_waitcnt lgkmcnt(7)
	global_store_dwordx4 v[68:69], v[88:91], off
	v_lshl_add_u64 v[68:69], v[68:69], 0, vcc
	s_waitcnt lgkmcnt(6)
	global_store_dwordx4 v[68:69], v[92:95], off
	v_lshl_add_u64 v[68:69], v[68:69], 0, vcc
	s_waitcnt lgkmcnt(5)
	global_store_dwordx4 v[68:69], v[96:99], off
	v_lshl_add_u64 v[68:69], v[68:69], 0, vcc
	s_waitcnt lgkmcnt(4)
	global_store_dwordx4 v[68:69], v[100:103], off
	v_lshl_add_u64 v[68:69], v[68:69], 0, vcc
	s_waitcnt lgkmcnt(3)
	global_store_dwordx4 v[68:69], v[104:107], off
	v_lshl_add_u64 v[68:69], v[68:69], 0, vcc
	s_waitcnt lgkmcnt(2)
	global_store_dwordx4 v[68:69], v[108:111], off
	v_lshl_add_u64 v[68:69], v[68:69], 0, vcc
	s_waitcnt lgkmcnt(1)
	global_store_dwordx4 v[68:69], v[112:115], off
	v_lshl_add_u64 v[68:69], v[68:69], 0, vcc
	s_waitcnt lgkmcnt(0)
	global_store_dwordx4 v[68:69], v[116:119], off
	s_add_i32 s35, s35, 1
	s_mov_b64 s[6:7], 0

; #define EPI_FOR(u) \
;     _Pragma("unroll") for (int ai = 0; ai < 2; ++ai) _Pragma("unroll") for (int m = 0; m < 4; ++m) _Pragma("unroll") for (int bj = 0; bj < 2; ++bj)
; #define EPI_COL(u) (EPI_CB(u) + 8 * fq)
;     DI void operator()(const Acc& acc, const Unit& u, int wr, int wc, int fr, int fq) const {
;         EPI_FOR(u) {
;             const int row = EPI_ROW(u), col = EPI_COL(u);
;             const float* rp = res + (size_t)row * 1024 + col; float* op = out + (size_t)row * 1024 + col;
;             const f32x4 r0 = *(const f32x4*)rp, r1 = *(const f32x4*)(rp + 4);
;             *(f32x4*)op = r0 + acc[ai][bj][m][0]; *(f32x4*)(op + 4) = r1 + acc[ai][bj][m][1];
;         }
;     }
.LBB0_1407:
	s_lshl_b32 s2, s40, 8
	s_add_i32 s2, s2, s47
	v_readlane_b32 s62, v254, 43
	v_add_u32_e32 v240, s2, v142
	s_lshl_b32 s2, s52, 8
	s_or_b32 s2, s2, s48
	v_lshl_add_u32 v241, v143, 3, s2
	s_mov_b64 s[6:7], -1
	s_andn2_b64 vcc, exec, s[10:11]
	v_readlane_b32 s63, v254, 44
	v_lshlrev_b32_e32 v186, 12, v240
	v_lshl_add_u32 v186, v241, 2, v186
	v_and_b32_e32 v242, 8, v233
	v_mul_u32_u24_e32 v243, 0xffe, v242
	v_sub_u32_e32 v186, v186, v243
	v_add_u32_e32 v187, 0x10000, v186
	v_add_u32_e32 v230, 0x20000, v186
	v_add_u32_e32 v231, 0x30000, v186
	v_add_u32_e32 v234, 0x8000, v186
	v_add_u32_e32 v235, 0x18000, v186
	v_add_u32_e32 v236, 0x28000, v186
	v_add_u32_e32 v237, 0x38000, v186
	global_load_dwordx4 v[138:141], v186, s[16:17]
	global_load_dwordx4 v[146:149], v234, s[16:17]
	global_load_dwordx4 v[150:153], v186, s[16:17] offset:512
	global_load_dwordx4 v[154:157], v234, s[16:17] offset:512
	global_load_dwordx4 v[158:161], v187, s[16:17]
	global_load_dwordx4 v[162:165], v235, s[16:17]
	global_load_dwordx4 v[166:169], v187, s[16:17] offset:512
	global_load_dwordx4 v[170:173], v235, s[16:17] offset:512
	global_load_dwordx4 v[174:177], v230, s[16:17]
	global_load_dwordx4 v[178:181], v236, s[16:17]
	global_load_dwordx4 v[182:185], v230, s[16:17] offset:512
	global_load_dwordx4 v[210:213], v236, s[16:17] offset:512
	global_load_dwordx4 v[214:217], v231, s[16:17]
	global_load_dwordx4 v[218:221], v237, s[16:17]
	global_load_dwordx4 v[222:225], v231, s[16:17] offset:512
	global_load_dwordx4 v[226:229], v237, s[16:17] offset:512
	s_waitcnt vmcnt(0)
	v_mov_b32_e32 v244, v138
	v_mov_b32_e32 v245, v139
	v_mov_b32_e32 v246, v140
	v_mov_b32_e32 v247, v141
	v_mov_b32_dpp v138, v146 row_ror:8 row_mask:0xf bank_mask:0xc
	v_mov_b32_dpp v139, v147 row_ror:8 row_mask:0xf bank_mask:0xc
	v_mov_b32_dpp v140, v148 row_ror:8 row_mask:0xf bank_mask:0xc
	v_mov_b32_dpp v141, v149 row_ror:8 row_mask:0xf bank_mask:0xc
	v_mov_b32_dpp v146, v244 row_ror:8 row_mask:0xf bank_mask:0x3
	v_mov_b32_dpp v147, v245 row_ror:8 row_mask:0xf bank_mask:0x3
	v_mov_b32_dpp v148, v246 row_ror:8 row_mask:0xf bank_mask:0x3
	v_mov_b32_dpp v149, v247 row_ror:8 row_mask:0xf bank_mask:0x3
	v_pk_add_f32 v[124:125], v[124:125], v[138:139]
	v_pk_add_f32 v[126:127], v[126:127], v[140:141]
	v_pk_add_f32 v[120:121], v[120:121], v[146:147]
	v_pk_add_f32 v[122:123], v[122:123], v[148:149]
	v_mov_b32_e32 v244, v120
	v_mov_b32_e32 v245, v121
	v_mov_b32_e32 v246, v122
	v_mov_b32_e32 v247, v123
	v_mov_b32_dpp v120, v124 row_ror:8 row_mask:0xf bank_mask:0x3
	v_mov_b32_dpp v121, v125 row_ror:8 row_mask:0xf bank_mask:0x3
	v_mov_b32_dpp v122, v126 row_ror:8 row_mask:0xf bank_mask:0x3
	v_mov_b32_dpp v123, v127 row_ror:8 row_mask:0xf bank_mask:0x3
	v_mov_b32_dpp v124, v244 row_ror:8 row_mask:0xf bank_mask:0xc
	v_mov_b32_dpp v125, v245 row_ror:8 row_mask:0xf bank_mask:0xc
	v_mov_b32_dpp v126, v246 row_ror:8 row_mask:0xf bank_mask:0xc
	v_mov_b32_dpp v127, v247 row_ror:8 row_mask:0xf bank_mask:0xc
	v_mov_b32_e32 v244, v150
	v_mov_b32_e32 v245, v151
	v_mov_b32_e32 v246, v152
	v_mov_b32_e32 v247, v153
	v_mov_b32_dpp v150, v154 row_ror:8 row_mask:0xf bank_mask:0xc
	v_mov_b32_dpp v151, v155 row_ror:8 row_mask:0xf bank_mask:0xc
	v_mov_b32_dpp v152, v156 row_ror:8 row_mask:0xf bank_mask:0xc
	v_mov_b32_dpp v153, v157 row_ror:8 row_mask:0xf bank_mask:0xc
	v_mov_b32_dpp v154, v244 row_ror:8 row_mask:0xf bank_mask:0x3
	v_mov_b32_dpp v155, v245 row_ror:8 row_mask:0xf bank_mask:0x3
	v_mov_b32_dpp v156, v246 row_ror:8 row_mask:0xf bank_mask:0x3
	v_mov_b32_dpp v157, v247 row_ror:8 row_mask:0xf bank_mask:0x3
	v_pk_add_f32 v[116:117], v[116:117], v[150:151]
	v_pk_add_f32 v[118:119], v[118:119], v[152:153]
	v_pk_add_f32 v[112:113], v[112:113], v[154:155]
	v_pk_add_f32 v[114:115], v[114:115], v[156:157]
	v_mov_b32_e32 v244, v112
	v_mov_b32_e32 v245, v113
	v_mov_b32_e32 v246, v114
	v_mov_b32_e32 v247, v115
	v_mov_b32_dpp v112, v116 row_ror:8 row_mask:0xf bank_mask:0x3
	v_mov_b32_dpp v113, v117 row_ror:8 row_mask:0xf bank_mask:0x3
	v_mov_b32_dpp v114, v118 row_ror:8 row_mask:0xf bank_mask:0x3
	v_mov_b32_dpp v115, v119 row_ror:8 row_mask:0xf bank_mask:0x3
	v_mov_b32_dpp v116, v244 row_ror:8 row_mask:0xf bank_mask:0xc
	v_mov_b32_dpp v117, v245 row_ror:8 row_mask:0xf bank_mask:0xc
	v_mov_b32_dpp v118, v246 row_ror:8 row_mask:0xf bank_mask:0xc
	v_mov_b32_dpp v119, v247 row_ror:8 row_mask:0xf bank_mask:0xc
	v_mov_b32_e32 v244, v158
	v_mov_b32_e32 v245, v159
	v_mov_b32_e32 v246, v160
	v_mov_b32_e32 v247, v161
	v_mov_b32_dpp v158, v162 row_ror:8 row_mask:0xf bank_mask:0xc
	v_mov_b32_dpp v159, v163 row_ror:8 row_mask:0xf bank_mask:0xc
	v_mov_b32_dpp v160, v164 row_ror:8 row_mask:0xf bank_mask:0xc
	v_mov_b32_dpp v161, v165 row_ror:8 row_mask:0xf bank_mask:0xc
	v_mov_b32_dpp v162, v244 row_ror:8 row_mask:0xf bank_mask:0x3
	v_mov_b32_dpp v163, v245 row_ror:8 row_mask:0xf bank_mask:0x3
	v_mov_b32_dpp v164, v246 row_ror:8 row_mask:0xf bank_mask:0x3
	v_mov_b32_dpp v165, v247 row_ror:8 row_mask:0xf bank_mask:0x3
	v_pk_add_f32 v[108:109], v[108:109], v[158:159]
	v_pk_add_f32 v[110:111], v[110:111], v[160:161]
	v_pk_add_f32 v[104:105], v[104:105], v[162:163]
	v_pk_add_f32 v[106:107], v[106:107], v[164:165]
	v_mov_b32_e32 v244, v104
	v_mov_b32_e32 v245, v105
	v_mov_b32_e32 v246, v106
	v_mov_b32_e32 v247, v107
	v_mov_b32_dpp v104, v108 row_ror:8 row_mask:0xf bank_mask:0x3
	v_mov_b32_dpp v105, v109 row_ror:8 row_mask:0xf bank_mask:0x3
	v_mov_b32_dpp v106, v110 row_ror:8 row_mask:0xf bank_mask:0x3
	v_mov_b32_dpp v107, v111 row_ror:8 row_mask:0xf bank_mask:0x3
	v_mov_b32_dpp v108, v244 row_ror:8 row_mask:0xf bank_mask:0xc
; #define EPI_FOR(u) \
;     _Pragma("unroll") for (int ai = 0; ai < 2; ++ai) _Pragma("unroll") for (int m = 0; m < 4; ++m) _Pragma("unroll") for (int bj = 0; bj < 2; ++bj)
; #define EPI_COL(u) (EPI_CB(u) + 8 * fq)
;     DI void operator()(const Acc& acc, const Unit& u, int wr, int wc, int fr, int fq) const {
;         EPI_FOR(u) {
;             const int row = EPI_ROW(u), col = EPI_COL(u);
;             const float* rp = res + (size_t)row * 1024 + col; float* op = out + (size_t)row * 1024 + col;
;             const f32x4 r0 = *(const f32x4*)rp, r1 = *(const f32x4*)(rp + 4);
;             *(f32x4*)op = r0 + acc[ai][bj][m][0]; *(f32x4*)(op + 4) = r1 + acc[ai][bj][m][1];
;         }
;     }
	v_mov_b32_dpp v109, v245 row_ror:8 row_mask:0xf bank_mask:0xc
	v_mov_b32_dpp v110, v246 row_ror:8 row_mask:0xf bank_mask:0xc
	v_mov_b32_dpp v111, v247 row_ror:8 row_mask:0xf bank_mask:0xc
	v_mov_b32_e32 v244, v166
	v_mov_b32_e32 v245, v167
	v_mov_b32_e32 v246, v168
	v_mov_b32_e32 v247, v169
	v_mov_b32_dpp v166, v170 row_ror:8 row_mask:0xf bank_mask:0xc
	v_mov_b32_dpp v167, v171 row_ror:8 row_mask:0xf bank_mask:0xc
	v_mov_b32_dpp v168, v172 row_ror:8 row_mask:0xf bank_mask:0xc
	v_mov_b32_dpp v169, v173 row_ror:8 row_mask:0xf bank_mask:0xc
	v_mov_b32_dpp v170, v244 row_ror:8 row_mask:0xf bank_mask:0x3
	v_mov_b32_dpp v171, v245 row_ror:8 row_mask:0xf bank_mask:0x3
	v_mov_b32_dpp v172, v246 row_ror:8 row_mask:0xf bank_mask:0x3
	v_mov_b32_dpp v173, v247 row_ror:8 row_mask:0xf bank_mask:0x3
	v_pk_add_f32 v[100:101], v[100:101], v[166:167]
	v_pk_add_f32 v[102:103], v[102:103], v[168:169]
	v_pk_add_f32 v[96:97], v[96:97], v[170:171]
	v_pk_add_f32 v[98:99], v[98:99], v[172:173]
	v_mov_b32_e32 v244, v96
	v_mov_b32_e32 v245, v97
	v_mov_b32_e32 v246, v98
	v_mov_b32_e32 v247, v99
	v_mov_b32_dpp v96, v100 row_ror:8 row_mask:0xf bank_mask:0x3
	v_mov_b32_dpp v97, v101 row_ror:8 row_mask:0xf bank_mask:0x3
	v_mov_b32_dpp v98, v102 row_ror:8 row_mask:0xf bank_mask:0x3
	v_mov_b32_dpp v99, v103 row_ror:8 row_mask:0xf bank_mask:0x3
	v_mov_b32_dpp v100, v244 row_ror:8 row_mask:0xf bank_mask:0xc
	v_mov_b32_dpp v101, v245 row_ror:8 row_mask:0xf bank_mask:0xc
	v_mov_b32_dpp v102, v246 row_ror:8 row_mask:0xf bank_mask:0xc
	v_mov_b32_dpp v103, v247 row_ror:8 row_mask:0xf bank_mask:0xc
	v_mov_b32_e32 v244, v174
	v_mov_b32_e32 v245, v175
	v_mov_b32_e32 v246, v176
	v_mov_b32_e32 v247, v177
	v_mov_b32_dpp v174, v178 row_ror:8 row_mask:0xf bank_mask:0xc
	v_mov_b32_dpp v175, v179 row_ror:8 row_mask:0xf bank_mask:0xc
	v_mov_b32_dpp v176, v180 row_ror:8 row_mask:0xf bank_mask:0xc
	v_mov_b32_dpp v177, v181 row_ror:8 row_mask:0xf bank_mask:0xc
	v_mov_b32_dpp v178, v244 row_ror:8 row_mask:0xf bank_mask:0x3
	v_mov_b32_dpp v179, v245 row_ror:8 row_mask:0xf bank_mask:0x3
	v_mov_b32_dpp v180, v246 row_ror:8 row_mask:0xf bank_mask:0x3
	v_mov_b32_dpp v181, v247 row_ror:8 row_mask:0xf bank_mask:0x3
	v_pk_add_f32 v[92:93], v[92:93], v[174:175]
	v_pk_add_f32 v[94:95], v[94:95], v[176:177]
	v_pk_add_f32 v[88:89], v[88:89], v[178:179]
	v_pk_add_f32 v[90:91], v[90:91], v[180:181]
	v_mov_b32_e32 v244, v88
	v_mov_b32_e32 v245, v89
	v_mov_b32_e32 v246, v90
	v_mov_b32_e32 v247, v91
	v_mov_b32_dpp v88, v92 row_ror:8 row_mask:0xf bank_mask:0x3
	v_mov_b32_dpp v89, v93 row_ror:8 row_mask:0xf bank_mask:0x3
	v_mov_b32_dpp v90, v94 row_ror:8 row_mask:0xf bank_mask:0x3
	v_mov_b32_dpp v91, v95 row_ror:8 row_mask:0xf bank_mask:0x3
	v_mov_b32_dpp v92, v244 row_ror:8 row_mask:0xf bank_mask:0xc
	v_mov_b32_dpp v93, v245 row_ror:8 row_mask:0xf bank_mask:0xc
	v_mov_b32_dpp v94, v246 row_ror:8 row_mask:0xf bank_mask:0xc
	v_mov_b32_dpp v95, v247 row_ror:8 row_mask:0xf bank_mask:0xc
	v_mov_b32_e32 v244, v182
	v_mov_b32_e32 v245, v183
	v_mov_b32_e32 v246, v184
	v_mov_b32_e32 v247, v185
	v_mov_b32_dpp v182, v210 row_ror:8 row_mask:0xf bank_mask:0xc
	v_mov_b32_dpp v183, v211 row_ror:8 row_mask:0xf bank_mask:0xc
	v_mov_b32_dpp v184, v212 row_ror:8 row_mask:0xf bank_mask:0xc
	v_mov_b32_dpp v185, v213 row_ror:8 row_mask:0xf bank_mask:0xc
	v_mov_b32_dpp v210, v244 row_ror:8 row_mask:0xf bank_mask:0x3
	v_mov_b32_dpp v211, v245 row_ror:8 row_mask:0xf bank_mask:0x3
	v_mov_b32_dpp v212, v246 row_ror:8 row_mask:0xf bank_mask:0x3
	v_mov_b32_dpp v213, v247 row_ror:8 row_mask:0xf bank_mask:0x3
	v_pk_add_f32 v[84:85], v[84:85], v[182:183]
	v_pk_add_f32 v[86:87], v[86:87], v[184:185]
	v_pk_add_f32 v[80:81], v[80:81], v[210:211]
	v_pk_add_f32 v[82:83], v[82:83], v[212:213]
	v_mov_b32_e32 v244, v80
	v_mov_b32_e32 v245, v81
	v_mov_b32_e32 v246, v82
	v_mov_b32_e32 v247, v83
	v_mov_b32_dpp v80, v84 row_ror:8 row_mask:0xf bank_mask:0x3
	v_mov_b32_dpp v81, v85 row_ror:8 row_mask:0xf bank_mask:0x3
	v_mov_b32_dpp v82, v86 row_ror:8 row_mask:0xf bank_mask:0x3
	v_mov_b32_dpp v83, v87 row_ror:8 row_mask:0xf bank_mask:0x3
	v_mov_b32_dpp v84, v244 row_ror:8 row_mask:0xf bank_mask:0xc
	v_mov_b32_dpp v85, v245 row_ror:8 row_mask:0xf bank_mask:0xc
	v_mov_b32_dpp v86, v246 row_ror:8 row_mask:0xf bank_mask:0xc
	v_mov_b32_dpp v87, v247 row_ror:8 row_mask:0xf bank_mask:0xc
	v_mov_b32_e32 v244, v214
	v_mov_b32_e32 v245, v215
	v_mov_b32_e32 v246, v216
	v_mov_b32_e32 v247, v217
	v_mov_b32_dpp v214, v218 row_ror:8 row_mask:0xf bank_mask:0xc
	v_mov_b32_dpp v215, v219 row_ror:8 row_mask:0xf bank_mask:0xc
	v_mov_b32_dpp v216, v220 row_ror:8 row_mask:0xf bank_mask:0xc
	v_mov_b32_dpp v217, v221 row_ror:8 row_mask:0xf bank_mask:0xc
	v_mov_b32_dpp v218, v244 row_ror:8 row_mask:0xf bank_mask:0x3
	v_mov_b32_dpp v219, v245 row_ror:8 row_mask:0xf bank_mask:0x3
	v_mov_b32_dpp v220, v246 row_ror:8 row_mask:0xf bank_mask:0x3
	v_mov_b32_dpp v221, v247 row_ror:8 row_mask:0xf bank_mask:0x3
	v_pk_add_f32 v[76:77], v[76:77], v[214:215]
	v_pk_add_f32 v[78:79], v[78:79], v[216:217]
	v_pk_add_f32 v[72:73], v[72:73], v[218:219]
	v_pk_add_f32 v[74:75], v[74:75], v[220:221]
	v_mov_b32_e32 v244, v72
	v_mov_b32_e32 v245, v73
	v_mov_b32_e32 v246, v74
	v_mov_b32_e32 v247, v75
	v_mov_b32_dpp v72, v76 row_ror:8 row_mask:0xf bank_mask:0x3
	v_mov_b32_dpp v73, v77 row_ror:8 row_mask:0xf bank_mask:0x3
	v_mov_b32_dpp v74, v78 row_ror:8 row_mask:0xf bank_mask:0x3
	v_mov_b32_dpp v75, v79 row_ror:8 row_mask:0xf bank_mask:0x3
	v_mov_b32_dpp v76, v244 row_ror:8 row_mask:0xf bank_mask:0xc
	v_mov_b32_dpp v77, v245 row_ror:8 row_mask:0xf bank_mask:0xc
	v_mov_b32_dpp v78, v246 row_ror:8 row_mask:0xf bank_mask:0xc
; #define EPI_FOR(u) \
;     _Pragma("unroll") for (int ai = 0; ai < 2; ++ai) _Pragma("unroll") for (int m = 0; m < 4; ++m) _Pragma("unroll") for (int bj = 0; bj < 2; ++bj)
; #define EPI_COL(u) (EPI_CB(u) + 8 * fq)
;     DI void operator()(const Acc& acc, const Unit& u, int wr, int wc, int fr, int fq) const {
;         EPI_FOR(u) {
;             const int row = EPI_ROW(u), col = EPI_COL(u);
;             const float* rp = res + (size_t)row * 1024 + col; float* op = out + (size_t)row * 1024 + col;
;             const f32x4 r0 = *(const f32x4*)rp, r1 = *(const f32x4*)(rp + 4);
;             *(f32x4*)op = r0 + acc[ai][bj][m][0]; *(f32x4*)(op + 4) = r1 + acc[ai][bj][m][1];
;         }
;     }
	v_mov_b32_dpp v79, v247 row_ror:8 row_mask:0xf bank_mask:0xc
	v_mov_b32_e32 v244, v222
	v_mov_b32_e32 v245, v223
	v_mov_b32_e32 v246, v224
	v_mov_b32_e32 v247, v225
	v_mov_b32_dpp v222, v226 row_ror:8 row_mask:0xf bank_mask:0xc
	v_mov_b32_dpp v223, v227 row_ror:8 row_mask:0xf bank_mask:0xc
	v_mov_b32_dpp v224, v228 row_ror:8 row_mask:0xf bank_mask:0xc
	v_mov_b32_dpp v225, v229 row_ror:8 row_mask:0xf bank_mask:0xc
	v_mov_b32_dpp v226, v244 row_ror:8 row_mask:0xf bank_mask:0x3
	v_mov_b32_dpp v227, v245 row_ror:8 row_mask:0xf bank_mask:0x3
	v_mov_b32_dpp v228, v246 row_ror:8 row_mask:0xf bank_mask:0x3
	v_mov_b32_dpp v229, v247 row_ror:8 row_mask:0xf bank_mask:0x3
	v_pk_add_f32 v[68:69], v[68:69], v[222:223]
	v_pk_add_f32 v[70:71], v[70:71], v[224:225]
	v_pk_add_f32 v[64:65], v[64:65], v[226:227]
	v_pk_add_f32 v[66:67], v[66:67], v[228:229]
	v_mov_b32_e32 v244, v64
	v_mov_b32_e32 v245, v65
	v_mov_b32_e32 v246, v66
	v_mov_b32_e32 v247, v67
	v_mov_b32_dpp v64, v68 row_ror:8 row_mask:0xf bank_mask:0x3
	v_mov_b32_dpp v65, v69 row_ror:8 row_mask:0xf bank_mask:0x3
	v_mov_b32_dpp v66, v70 row_ror:8 row_mask:0xf bank_mask:0x3
	v_mov_b32_dpp v67, v71 row_ror:8 row_mask:0xf bank_mask:0x3
	v_mov_b32_dpp v68, v244 row_ror:8 row_mask:0xf bank_mask:0xc
	v_mov_b32_dpp v69, v245 row_ror:8 row_mask:0xf bank_mask:0xc
	v_mov_b32_dpp v70, v246 row_ror:8 row_mask:0xf bank_mask:0xc
	v_mov_b32_dpp v71, v247 row_ror:8 row_mask:0xf bank_mask:0xc
	global_store_dwordx4 v186, v[124:127], s[16:17]
	global_store_dwordx4 v234, v[120:123], s[16:17]
	global_store_dwordx4 v186, v[116:119], s[16:17] offset:512
	global_store_dwordx4 v234, v[112:115], s[16:17] offset:512
	global_store_dwordx4 v187, v[108:111], s[16:17]
	global_store_dwordx4 v235, v[104:107], s[16:17]
	global_store_dwordx4 v187, v[100:103], s[16:17] offset:512
	global_store_dwordx4 v235, v[96:99], s[16:17] offset:512
	global_store_dwordx4 v230, v[92:95], s[16:17]
	global_store_dwordx4 v236, v[88:91], s[16:17]
	global_store_dwordx4 v230, v[84:87], s[16:17] offset:512
	global_store_dwordx4 v236, v[80:83], s[16:17] offset:512
	global_store_dwordx4 v231, v[76:79], s[16:17]
	global_store_dwordx4 v237, v[72:75], s[16:17]
	global_store_dwordx4 v231, v[68:71], s[16:17] offset:512
	global_store_dwordx4 v237, v[64:67], s[16:17] offset:512
	v_add_u32_e32 v186, 0x80000, v186
	v_add_u32_e32 v187, 0x80000, v187
	v_add_u32_e32 v230, 0x80000, v230
	v_add_u32_e32 v231, 0x80000, v231
	v_add_u32_e32 v234, 0x80000, v234
	v_add_u32_e32 v235, 0x80000, v235
	v_add_u32_e32 v236, 0x80000, v236
	v_add_u32_e32 v237, 0x80000, v237
	global_load_dwordx4 v[138:141], v186, s[16:17]
	global_load_dwordx4 v[146:149], v234, s[16:17]
	global_load_dwordx4 v[150:153], v186, s[16:17] offset:512
	global_load_dwordx4 v[154:157], v234, s[16:17] offset:512
	global_load_dwordx4 v[158:161], v187, s[16:17]
	global_load_dwordx4 v[162:165], v235, s[16:17]
	global_load_dwordx4 v[166:169], v187, s[16:17] offset:512
	global_load_dwordx4 v[170:173], v235, s[16:17] offset:512
	global_load_dwordx4 v[174:177], v230, s[16:17]
	global_load_dwordx4 v[178:181], v236, s[16:17]
	global_load_dwordx4 v[182:185], v230, s[16:17] offset:512
	global_load_dwordx4 v[210:213], v236, s[16:17] offset:512
	global_load_dwordx4 v[214:217], v231, s[16:17]
	global_load_dwordx4 v[218:221], v237, s[16:17]
	global_load_dwordx4 v[222:225], v231, s[16:17] offset:512
	global_load_dwordx4 v[226:229], v237, s[16:17] offset:512
	s_waitcnt vmcnt(0)
	v_mov_b32_e32 v244, v138
	v_mov_b32_e32 v245, v139
	v_mov_b32_e32 v246, v140
	v_mov_b32_e32 v247, v141
	v_mov_b32_dpp v138, v146 row_ror:8 row_mask:0xf bank_mask:0xc
	v_mov_b32_dpp v139, v147 row_ror:8 row_mask:0xf bank_mask:0xc
	v_mov_b32_dpp v140, v148 row_ror:8 row_mask:0xf bank_mask:0xc
	v_mov_b32_dpp v141, v149 row_ror:8 row_mask:0xf bank_mask:0xc
	v_mov_b32_dpp v146, v244 row_ror:8 row_mask:0xf bank_mask:0x3
	v_mov_b32_dpp v147, v245 row_ror:8 row_mask:0xf bank_mask:0x3
	v_mov_b32_dpp v148, v246 row_ror:8 row_mask:0xf bank_mask:0x3
	v_mov_b32_dpp v149, v247 row_ror:8 row_mask:0xf bank_mask:0x3
	v_pk_add_f32 v[60:61], v[60:61], v[138:139]
	v_pk_add_f32 v[62:63], v[62:63], v[140:141]
	v_pk_add_f32 v[56:57], v[56:57], v[146:147]
	v_pk_add_f32 v[58:59], v[58:59], v[148:149]
	v_mov_b32_e32 v244, v56
	v_mov_b32_e32 v245, v57
	v_mov_b32_e32 v246, v58
	v_mov_b32_e32 v247, v59
	v_mov_b32_dpp v56, v60 row_ror:8 row_mask:0xf bank_mask:0x3
	v_mov_b32_dpp v57, v61 row_ror:8 row_mask:0xf bank_mask:0x3
	v_mov_b32_dpp v58, v62 row_ror:8 row_mask:0xf bank_mask:0x3
	v_mov_b32_dpp v59, v63 row_ror:8 row_mask:0xf bank_mask:0x3
	v_mov_b32_dpp v60, v244 row_ror:8 row_mask:0xf bank_mask:0xc
	v_mov_b32_dpp v61, v245 row_ror:8 row_mask:0xf bank_mask:0xc
	v_mov_b32_dpp v62, v246 row_ror:8 row_mask:0xf bank_mask:0xc
	v_mov_b32_dpp v63, v247 row_ror:8 row_mask:0xf bank_mask:0xc
	v_mov_b32_e32 v244, v150
	v_mov_b32_e32 v245, v151
	v_mov_b32_e32 v246, v152
	v_mov_b32_e32 v247, v153
	v_mov_b32_dpp v150, v154 row_ror:8 row_mask:0xf bank_mask:0xc
	v_mov_b32_dpp v151, v155 row_ror:8 row_mask:0xf bank_mask:0xc
	v_mov_b32_dpp v152, v156 row_ror:8 row_mask:0xf bank_mask:0xc
	v_mov_b32_dpp v153, v157 row_ror:8 row_mask:0xf bank_mask:0xc
	v_mov_b32_dpp v154, v244 row_ror:8 row_mask:0xf bank_mask:0x3
	v_mov_b32_dpp v155, v245 row_ror:8 row_mask:0xf bank_mask:0x3
	v_mov_b32_dpp v156, v246 row_ror:8 row_mask:0xf bank_mask:0x3
	v_mov_b32_dpp v157, v247 row_ror:8 row_mask:0xf bank_mask:0x3
	v_pk_add_f32 v[52:53], v[52:53], v[150:151]
	v_pk_add_f32 v[54:55], v[54:55], v[152:153]
	v_pk_add_f32 v[48:49], v[48:49], v[154:155]
	v_pk_add_f32 v[50:51], v[50:51], v[156:157]
	v_mov_b32_e32 v244, v48
; #define EPI_FOR(u) \
;     _Pragma("unroll") for (int ai = 0; ai < 2; ++ai) _Pragma("unroll") for (int m = 0; m < 4; ++m) _Pragma("unroll") for (int bj = 0; bj < 2; ++bj)
; #define EPI_COL(u) (EPI_CB(u) + 8 * fq)
;     DI void operator()(const Acc& acc, const Unit& u, int wr, int wc, int fr, int fq) const {
;         EPI_FOR(u) {
;             const int row = EPI_ROW(u), col = EPI_COL(u);
;             const float* rp = res + (size_t)row * 1024 + col; float* op = out + (size_t)row * 1024 + col;
;             const f32x4 r0 = *(const f32x4*)rp, r1 = *(const f32x4*)(rp + 4);
;             *(f32x4*)op = r0 + acc[ai][bj][m][0]; *(f32x4*)(op + 4) = r1 + acc[ai][bj][m][1];
;         }
;     }
	v_mov_b32_e32 v245, v49
	v_mov_b32_e32 v246, v50
	v_mov_b32_e32 v247, v51
	v_mov_b32_dpp v48, v52 row_ror:8 row_mask:0xf bank_mask:0x3
	v_mov_b32_dpp v49, v53 row_ror:8 row_mask:0xf bank_mask:0x3
	v_mov_b32_dpp v50, v54 row_ror:8 row_mask:0xf bank_mask:0x3
	v_mov_b32_dpp v51, v55 row_ror:8 row_mask:0xf bank_mask:0x3
	v_mov_b32_dpp v52, v244 row_ror:8 row_mask:0xf bank_mask:0xc
	v_mov_b32_dpp v53, v245 row_ror:8 row_mask:0xf bank_mask:0xc
	v_mov_b32_dpp v54, v246 row_ror:8 row_mask:0xf bank_mask:0xc
	v_mov_b32_dpp v55, v247 row_ror:8 row_mask:0xf bank_mask:0xc
	v_mov_b32_e32 v244, v158
	v_mov_b32_e32 v245, v159
	v_mov_b32_e32 v246, v160
	v_mov_b32_e32 v247, v161
	v_mov_b32_dpp v158, v162 row_ror:8 row_mask:0xf bank_mask:0xc
	v_mov_b32_dpp v159, v163 row_ror:8 row_mask:0xf bank_mask:0xc
	v_mov_b32_dpp v160, v164 row_ror:8 row_mask:0xf bank_mask:0xc
	v_mov_b32_dpp v161, v165 row_ror:8 row_mask:0xf bank_mask:0xc
	v_mov_b32_dpp v162, v244 row_ror:8 row_mask:0xf bank_mask:0x3
	v_mov_b32_dpp v163, v245 row_ror:8 row_mask:0xf bank_mask:0x3
	v_mov_b32_dpp v164, v246 row_ror:8 row_mask:0xf bank_mask:0x3
	v_mov_b32_dpp v165, v247 row_ror:8 row_mask:0xf bank_mask:0x3
	v_pk_add_f32 v[44:45], v[44:45], v[158:159]
	v_pk_add_f32 v[46:47], v[46:47], v[160:161]
	v_pk_add_f32 v[40:41], v[40:41], v[162:163]
	v_pk_add_f32 v[42:43], v[42:43], v[164:165]
	v_mov_b32_e32 v244, v40
	v_mov_b32_e32 v245, v41
	v_mov_b32_e32 v246, v42
	v_mov_b32_e32 v247, v43
	v_mov_b32_dpp v40, v44 row_ror:8 row_mask:0xf bank_mask:0x3
	v_mov_b32_dpp v41, v45 row_ror:8 row_mask:0xf bank_mask:0x3
	v_mov_b32_dpp v42, v46 row_ror:8 row_mask:0xf bank_mask:0x3
	v_mov_b32_dpp v43, v47 row_ror:8 row_mask:0xf bank_mask:0x3
	v_mov_b32_dpp v44, v244 row_ror:8 row_mask:0xf bank_mask:0xc
	v_mov_b32_dpp v45, v245 row_ror:8 row_mask:0xf bank_mask:0xc
	v_mov_b32_dpp v46, v246 row_ror:8 row_mask:0xf bank_mask:0xc
	v_mov_b32_dpp v47, v247 row_ror:8 row_mask:0xf bank_mask:0xc
	v_mov_b32_e32 v244, v166
	v_mov_b32_e32 v245, v167
	v_mov_b32_e32 v246, v168
	v_mov_b32_e32 v247, v169
	v_mov_b32_dpp v166, v170 row_ror:8 row_mask:0xf bank_mask:0xc
	v_mov_b32_dpp v167, v171 row_ror:8 row_mask:0xf bank_mask:0xc
	v_mov_b32_dpp v168, v172 row_ror:8 row_mask:0xf bank_mask:0xc
	v_mov_b32_dpp v169, v173 row_ror:8 row_mask:0xf bank_mask:0xc
	v_mov_b32_dpp v170, v244 row_ror:8 row_mask:0xf bank_mask:0x3
	v_mov_b32_dpp v171, v245 row_ror:8 row_mask:0xf bank_mask:0x3
	v_mov_b32_dpp v172, v246 row_ror:8 row_mask:0xf bank_mask:0x3
	v_mov_b32_dpp v173, v247 row_ror:8 row_mask:0xf bank_mask:0x3
	v_pk_add_f32 v[36:37], v[36:37], v[166:167]
	v_pk_add_f32 v[38:39], v[38:39], v[168:169]
	v_pk_add_f32 v[32:33], v[32:33], v[170:171]
	v_pk_add_f32 v[34:35], v[34:35], v[172:173]
	v_mov_b32_e32 v244, v32
	v_mov_b32_e32 v245, v33
	v_mov_b32_e32 v246, v34
	v_mov_b32_e32 v247, v35
	v_mov_b32_dpp v32, v36 row_ror:8 row_mask:0xf bank_mask:0x3
	v_mov_b32_dpp v33, v37 row_ror:8 row_mask:0xf bank_mask:0x3
	v_mov_b32_dpp v34, v38 row_ror:8 row_mask:0xf bank_mask:0x3
	v_mov_b32_dpp v35, v39 row_ror:8 row_mask:0xf bank_mask:0x3
	v_mov_b32_dpp v36, v244 row_ror:8 row_mask:0xf bank_mask:0xc
	v_mov_b32_dpp v37, v245 row_ror:8 row_mask:0xf bank_mask:0xc
	v_mov_b32_dpp v38, v246 row_ror:8 row_mask:0xf bank_mask:0xc
	v_mov_b32_dpp v39, v247 row_ror:8 row_mask:0xf bank_mask:0xc
	v_mov_b32_e32 v244, v174
	v_mov_b32_e32 v245, v175
	v_mov_b32_e32 v246, v176
	v_mov_b32_e32 v247, v177
	v_mov_b32_dpp v174, v178 row_ror:8 row_mask:0xf bank_mask:0xc
	v_mov_b32_dpp v175, v179 row_ror:8 row_mask:0xf bank_mask:0xc
	v_mov_b32_dpp v176, v180 row_ror:8 row_mask:0xf bank_mask:0xc
	v_mov_b32_dpp v177, v181 row_ror:8 row_mask:0xf bank_mask:0xc
	v_mov_b32_dpp v178, v244 row_ror:8 row_mask:0xf bank_mask:0x3
	v_mov_b32_dpp v179, v245 row_ror:8 row_mask:0xf bank_mask:0x3
	v_mov_b32_dpp v180, v246 row_ror:8 row_mask:0xf bank_mask:0x3
	v_mov_b32_dpp v181, v247 row_ror:8 row_mask:0xf bank_mask:0x3
	v_pk_add_f32 v[28:29], v[28:29], v[174:175]
	v_pk_add_f32 v[30:31], v[30:31], v[176:177]
	v_pk_add_f32 v[24:25], v[24:25], v[178:179]
	v_pk_add_f32 v[26:27], v[26:27], v[180:181]
	v_mov_b32_e32 v244, v24
	v_mov_b32_e32 v245, v25
	v_mov_b32_e32 v246, v26
	v_mov_b32_e32 v247, v27
	v_mov_b32_dpp v24, v28 row_ror:8 row_mask:0xf bank_mask:0x3
	v_mov_b32_dpp v25, v29 row_ror:8 row_mask:0xf bank_mask:0x3
	v_mov_b32_dpp v26, v30 row_ror:8 row_mask:0xf bank_mask:0x3
	v_mov_b32_dpp v27, v31 row_ror:8 row_mask:0xf bank_mask:0x3
	v_mov_b32_dpp v28, v244 row_ror:8 row_mask:0xf bank_mask:0xc
	v_mov_b32_dpp v29, v245 row_ror:8 row_mask:0xf bank_mask:0xc
	v_mov_b32_dpp v30, v246 row_ror:8 row_mask:0xf bank_mask:0xc
	v_mov_b32_dpp v31, v247 row_ror:8 row_mask:0xf bank_mask:0xc
	v_mov_b32_e32 v244, v182
	v_mov_b32_e32 v245, v183
	v_mov_b32_e32 v246, v184
	v_mov_b32_e32 v247, v185
	v_mov_b32_dpp v182, v210 row_ror:8 row_mask:0xf bank_mask:0xc
; #define PG8_BAR __builtin_amdgcn_s_barrier()
; #define EPI_FOR(u) \
;     _Pragma("unroll") for (int ai = 0; ai < 2; ++ai) _Pragma("unroll") for (int m = 0; m < 4; ++m) _Pragma("unroll") for (int bj = 0; bj < 2; ++bj)
; #define EPI_COL(u) (EPI_CB(u) + 8 * fq)
; template <class Epi>
; DI void gemm_phase(LAS unsigned char* lds, const Gemm g, const Sched& S, const Epi& E) {
;     ...
;         if (!has_next) break;
; #pragma unroll
;         for (int a = 0; a < 2; ++a)
; #pragma unroll
;             for (int b = 0; b < 2; ++b)
; #pragma unroll
;                 for (int m = 0; m < 4; ++m)
; #pragma unroll
;                     for (int n = 0; n < 2; ++n) acc[a][b][m][n] = (f32x4){0.f, 0.f, 0.f, 0.f};
;         cur = nxt; cA = nA; cB = nB; ++ui;
;         if (wr == 1) PG8_BAR;
;     DI void operator()(const Acc& acc, const Unit& u, int wr, int wc, int fr, int fq) const {
;         EPI_FOR(u) {
;             const int row = EPI_ROW(u), col = EPI_COL(u);
;             const float* rp = res + (size_t)row * 1024 + col; float* op = out + (size_t)row * 1024 + col;
;             const f32x4 r0 = *(const f32x4*)rp, r1 = *(const f32x4*)(rp + 4);
;             *(f32x4*)op = r0 + acc[ai][bj][m][0]; *(f32x4*)(op + 4) = r1 + acc[ai][bj][m][1];
;         }
;     }
	v_mov_b32_dpp v183, v211 row_ror:8 row_mask:0xf bank_mask:0xc
	v_mov_b32_dpp v184, v212 row_ror:8 row_mask:0xf bank_mask:0xc
	v_mov_b32_dpp v185, v213 row_ror:8 row_mask:0xf bank_mask:0xc
	v_mov_b32_dpp v210, v244 row_ror:8 row_mask:0xf bank_mask:0x3
	v_mov_b32_dpp v211, v245 row_ror:8 row_mask:0xf bank_mask:0x3
	v_mov_b32_dpp v212, v246 row_ror:8 row_mask:0xf bank_mask:0x3
	v_mov_b32_dpp v213, v247 row_ror:8 row_mask:0xf bank_mask:0x3
	v_pk_add_f32 v[20:21], v[20:21], v[182:183]
	v_pk_add_f32 v[22:23], v[22:23], v[184:185]
	v_pk_add_f32 v[16:17], v[16:17], v[210:211]
	v_pk_add_f32 v[18:19], v[18:19], v[212:213]
	v_mov_b32_e32 v244, v16
	v_mov_b32_e32 v245, v17
	v_mov_b32_e32 v246, v18
	v_mov_b32_e32 v247, v19
	v_mov_b32_dpp v16, v20 row_ror:8 row_mask:0xf bank_mask:0x3
	v_mov_b32_dpp v17, v21 row_ror:8 row_mask:0xf bank_mask:0x3
	v_mov_b32_dpp v18, v22 row_ror:8 row_mask:0xf bank_mask:0x3
	v_mov_b32_dpp v19, v23 row_ror:8 row_mask:0xf bank_mask:0x3
	v_mov_b32_dpp v20, v244 row_ror:8 row_mask:0xf bank_mask:0xc
	v_mov_b32_dpp v21, v245 row_ror:8 row_mask:0xf bank_mask:0xc
	v_mov_b32_dpp v22, v246 row_ror:8 row_mask:0xf bank_mask:0xc
	v_mov_b32_dpp v23, v247 row_ror:8 row_mask:0xf bank_mask:0xc
	v_mov_b32_e32 v244, v214
	v_mov_b32_e32 v245, v215
	v_mov_b32_e32 v246, v216
	v_mov_b32_e32 v247, v217
	v_mov_b32_dpp v214, v218 row_ror:8 row_mask:0xf bank_mask:0xc
	v_mov_b32_dpp v215, v219 row_ror:8 row_mask:0xf bank_mask:0xc
	v_mov_b32_dpp v216, v220 row_ror:8 row_mask:0xf bank_mask:0xc
	v_mov_b32_dpp v217, v221 row_ror:8 row_mask:0xf bank_mask:0xc
	v_mov_b32_dpp v218, v244 row_ror:8 row_mask:0xf bank_mask:0x3
	v_mov_b32_dpp v219, v245 row_ror:8 row_mask:0xf bank_mask:0x3
	v_mov_b32_dpp v220, v246 row_ror:8 row_mask:0xf bank_mask:0x3
	v_mov_b32_dpp v221, v247 row_ror:8 row_mask:0xf bank_mask:0x3
	v_pk_add_f32 v[12:13], v[12:13], v[214:215]
	v_pk_add_f32 v[14:15], v[14:15], v[216:217]
	v_pk_add_f32 v[8:9], v[8:9], v[218:219]
	v_pk_add_f32 v[10:11], v[10:11], v[220:221]
	v_mov_b32_e32 v244, v8
	v_mov_b32_e32 v245, v9
	v_mov_b32_e32 v246, v10
	v_mov_b32_e32 v247, v11
	v_mov_b32_dpp v8, v12 row_ror:8 row_mask:0xf bank_mask:0x3
	v_mov_b32_dpp v9, v13 row_ror:8 row_mask:0xf bank_mask:0x3
	v_mov_b32_dpp v10, v14 row_ror:8 row_mask:0xf bank_mask:0x3
	v_mov_b32_dpp v11, v15 row_ror:8 row_mask:0xf bank_mask:0x3
	v_mov_b32_dpp v12, v244 row_ror:8 row_mask:0xf bank_mask:0xc
	v_mov_b32_dpp v13, v245 row_ror:8 row_mask:0xf bank_mask:0xc
	v_mov_b32_dpp v14, v246 row_ror:8 row_mask:0xf bank_mask:0xc
	v_mov_b32_dpp v15, v247 row_ror:8 row_mask:0xf bank_mask:0xc
	v_mov_b32_e32 v244, v222
	v_mov_b32_e32 v245, v223
	v_mov_b32_e32 v246, v224
	v_mov_b32_e32 v247, v225
	v_mov_b32_dpp v222, v226 row_ror:8 row_mask:0xf bank_mask:0xc
	v_mov_b32_dpp v223, v227 row_ror:8 row_mask:0xf bank_mask:0xc
	v_mov_b32_dpp v224, v228 row_ror:8 row_mask:0xf bank_mask:0xc
	v_mov_b32_dpp v225, v229 row_ror:8 row_mask:0xf bank_mask:0xc
	v_mov_b32_dpp v226, v244 row_ror:8 row_mask:0xf bank_mask:0x3
	v_mov_b32_dpp v227, v245 row_ror:8 row_mask:0xf bank_mask:0x3
	v_mov_b32_dpp v228, v246 row_ror:8 row_mask:0xf bank_mask:0x3
	v_mov_b32_dpp v229, v247 row_ror:8 row_mask:0xf bank_mask:0x3
	v_pk_add_f32 v[4:5], v[4:5], v[222:223]
	v_pk_add_f32 v[6:7], v[6:7], v[224:225]
	v_pk_add_f32 v[0:1], v[0:1], v[226:227]
	v_pk_add_f32 v[2:3], v[2:3], v[228:229]
	v_mov_b32_e32 v244, v0
	v_mov_b32_e32 v245, v1
	v_mov_b32_e32 v246, v2
	v_mov_b32_e32 v247, v3
	v_mov_b32_dpp v0, v4 row_ror:8 row_mask:0xf bank_mask:0x3
	v_mov_b32_dpp v1, v5 row_ror:8 row_mask:0xf bank_mask:0x3
	v_mov_b32_dpp v2, v6 row_ror:8 row_mask:0xf bank_mask:0x3
	v_mov_b32_dpp v3, v7 row_ror:8 row_mask:0xf bank_mask:0x3
	v_mov_b32_dpp v4, v244 row_ror:8 row_mask:0xf bank_mask:0xc
	v_mov_b32_dpp v5, v245 row_ror:8 row_mask:0xf bank_mask:0xc
	v_mov_b32_dpp v6, v246 row_ror:8 row_mask:0xf bank_mask:0xc
	v_mov_b32_dpp v7, v247 row_ror:8 row_mask:0xf bank_mask:0xc
	global_store_dwordx4 v186, v[60:63], s[16:17]
	global_store_dwordx4 v234, v[56:59], s[16:17]
	global_store_dwordx4 v186, v[52:55], s[16:17] offset:512
	global_store_dwordx4 v234, v[48:51], s[16:17] offset:512
	global_store_dwordx4 v187, v[44:47], s[16:17]
	global_store_dwordx4 v235, v[40:43], s[16:17]
	global_store_dwordx4 v187, v[36:39], s[16:17] offset:512
	global_store_dwordx4 v235, v[32:35], s[16:17] offset:512
	global_store_dwordx4 v230, v[28:31], s[16:17]
	global_store_dwordx4 v236, v[24:27], s[16:17]
	global_store_dwordx4 v230, v[20:23], s[16:17] offset:512
	global_store_dwordx4 v236, v[16:19], s[16:17] offset:512
	global_store_dwordx4 v231, v[12:15], s[16:17]
	global_store_dwordx4 v237, v[8:11], s[16:17]
	global_store_dwordx4 v231, v[4:7], s[16:17] offset:512
	global_store_dwordx4 v237, v[0:3], s[16:17] offset:512
	s_cbranch_vccnz .LBB0_1396
	s_andn2_b64 vcc, exec, s[12:13]
	s_cbranch_vccnz .LBB0_1395
	s_barrier
	s_branch .LBB0_1395
